# X34: grid-barrier seams with XCD-local dependencies (gate|up->down, FFN2 down->next gate|up, w_out->gate|up) skip the cross-XCD step when a run-time census shows workgroup index mod 8 maps one-to-one
# speedup vs baseline: 1.0008x; 1.0008x over previous
; #define LAS __attribute__((address_space(3)))
; __device__ __forceinline__ unsigned xb_add(unsigned* p, unsigned v) { return __hip_atomic_fetch_add(p, v, __ATOMIC_RELAXED, __HIP_MEMORY_SCOPE_AGENT); }
; __device__ __forceinline__ unsigned xb_xcc_id() { return (unsigned)__builtin_amdgcn_s_getreg((3 << 11) | 20) & 0xFu; }
; __device__ __forceinline__ XcdBarrier xcd_barrier_post(unsigned* bar, volatile LAS unsigned* st) {
;     XcdBarrier b; b.bar = bar; b.x = xb_xcc_id(); b.st = st;
;     if (threadIdx.x == 0) (void)xb_add(&bar[XB_XCNT(b.x)], 1u);
;     return b;
; }
.LBB0_8:
	s_or_b64 exec, exec, s[0:1]
	v_readlane_b32 s0, v252, 0
	v_readlane_b32 s1, v252, 1
	s_sub_i32 s0, s1, s0
	s_add_u32 s20, s78, 0x1000
	s_addc_u32 s21, s79, 0
	s_cmp_lt_i32 s0, 2
	s_mov_b32 s0, 0
	s_mov_b32 s2, 0
	v_cmp_eq_u32_e32 vcc, 0, v0
	v_writelane_b32 v252, s0, 37
	s_waitcnt lgkmcnt(0)
	s_barrier
	s_cbranch_scc1 .LBB0_13
	s_getreg_b32 s0, hwreg(HW_REG_XCC_ID, 0, 4)
	s_and_b32 s2, s0, 15
	s_and_saveexec_b64 s[0:1], vcc
	s_cbranch_execz .LBB0_12
	s_mov_b64 s[22:23], exec
	v_mbcnt_lo_u32_b32 v2, s22, 0
	v_mbcnt_hi_u32_b32 v2, s23, v2
	v_cmp_eq_u32_e32 vcc, 0, v2
	s_and_b64 s[24:25], exec, vcc
	s_mov_b64 exec, s[24:25]
	s_cbranch_execz .LBB0_12
	s_lshl_b32 s3, s2, 8
	s_bcnt1_i32_b64 s22, s[22:23]
	v_mov_b32_e32 v2, s3
	v_mov_b32_e32 v3, s22
	global_atomic_add v2, v3, s[20:21] offset:1024
	v_readlane_b32 s22, v252, 4
	s_and_b32 s22, s22, 7
	s_sub_i32 s22, s2, s22
	s_and_b32 s22, s22, 15
	s_lshl_b32 s22, 1, s22
	s_nop 1
	v_mov_b32_e32 v3, s22
	v_mov_b32_e32 v2, 0
	global_atomic_or v2, v3, s[20:21] offset:516

; __device__ __forceinline__ void xcd_barrier_complete(unsigned* bar, unsigned x, unsigned& nloc, unsigned& nx) {
;     const unsigned G = gridDim.x * gridDim.y * gridDim.z;
;     unsigned sum, cnt, mine, sp = 0u;
;     for (;;) {
;         sum = 0u; cnt = 0u; mine = 0u;
; #pragma unroll
;         for (unsigned j = 0; j < 16; ++j) { const unsigned c = xb_ld(&bar[XB_XCNT(j)]); sum += c; cnt += (c > 0u) ? 1u : 0u; mine = (j == x) ? c : mine; }
;         if (sum == G) break;
;         __builtin_amdgcn_s_sleep(1);
;         if ((++sp & 255u) == 0u) { if (xb_ld(&bar[XB_TMO])) break; if (sp > XB_SPIN_CAP) { atomicAdd(&bar[XB_TMO], 1u); break; } }
;     }
;     nloc = mine > 0u ? mine : 1u; nx = cnt > 0u ? cnt : 1u;
; }
; __device__ __forceinline__ void xcd_barrier(const XcdBarrier& b) {
;     asm volatile("s_waitcnt vmcnt(0)" ::: "memory");
;     __syncthreads();
;     if (threadIdx.x == 0) {
;         unsigned* bar = b.bar;
;         __builtin_amdgcn_s_waitcnt(0);
;         unsigned nloc = b.st[0], nx = b.st[1];
;         if (nloc == 0u) { xcd_barrier_complete(bar, b.x, nloc, nx); b.st[0] = nloc; b.st[1] = nx; }
;         const unsigned old = xb_add(&bar[XB_XSUB(b.x)], 1u);
;         const unsigned gen = old / nloc;
;         if (old + 1u == (gen + 1u) * nloc) {
;             __builtin_amdgcn_fence(__ATOMIC_RELEASE, "agent");
;             asm volatile("s_waitcnt vmcnt(0)" ::: "memory");
;             const unsigned og = xb_add(&bar[XB_TOP], 1u);
; __global__ void __launch_bounds__(NTHR, 2) fwd_kernel(Args args) {
;     ...
;     for (int f = 0; f < 2 * DEPTH; ++f) {
;         const int l = f >> 1, second = f & 1, base = 1 + 8 * f;
;         unsigned long long wsv_ = (unsigned long long)args.ws, outv_ = (unsigned long long)args.out; asm volatile("" : "+s"(wsv_), "+s"(outv_));
;         unsigned char* ws = (unsigned char*)(GAS unsigned char*)wsv_; float* out = (float*)(GAS float*)outv_; rs_t* rowss_all = (rs_t*)(ws + WS_ROWSS);
;         int tid = tid0; asm volatile("" : "+v"(tid));
;         const int lane = tid & 63, wave = __builtin_amdgcn_readfirstlane(tid >> 6), gw = vcu * NWAVES + wave;
;         bf16* XB = (bf16*)(ws + WS_XB); bf16* HP = (bf16*)(ws + WS_HP); bf16* Y = (bf16*)(ws + WS_Y);
;         const rs_t* rs_in = rowss_all + (size_t)(3 * l + 2 * second) * M;
;         rs_t* rs_out = rowss_all + (size_t)(3 * l + 1 + 2 * second) * M;
.LBB0_198:
	v_readlane_b32 s5, v252, 4
	s_cmpk_lt_i32 s5, 0x1600
	s_cselect_b64 s[0:1], -1, 0
	v_writelane_b32 v252, s0, 56
	s_ashr_i32 s4, s5, 31
	s_ashr_i32 s63, s62, 31
	v_writelane_b32 v252, s1, 57
	s_lshr_b32 s0, s4, 29
	s_add_i32 s1, s5, s0
	s_ashr_i32 s0, s1, 3
	s_and_b32 s1, s1, -8
	s_sub_i32 s1, s5, s1
	s_add_u32 s6, s78, 0x1200
	s_addc_u32 s7, s79, 0
	v_writelane_b32 v252, s6, 58
	s_waitcnt lgkmcnt(0)
	v_mov_b32_e32 v5, 0
	v_mov_b32_e32 v194, 0x358637bd
	v_writelane_b32 v252, s7, 59
	s_add_u32 s6, s78, 0x1400
	s_addc_u32 s7, s79, 0
	v_writelane_b32 v252, s6, 60
	v_mov_b32_e32 v195, 1
	v_mov_b32_e32 v196, 0x3ecc95a3
	v_writelane_b32 v252, s7, 61
	s_add_u32 s6, s78, 0x1500
	s_addc_u32 s7, s79, 0
	v_writelane_b32 v252, s6, 62
	v_mov_b32_e32 v197, 0x3d2aaaab
	v_mov_b32_e32 v198, 0x260
	v_writelane_b32 v252, s7, 63
	s_add_u32 s6, s78, 0x1600
	s_addc_u32 s7, s79, 0
	v_writelane_b32 v253, s6, 0
	v_mov_b32_e32 v159, 0x41000000
	v_mov_b64_e32 v[160:161], 0xbff
	v_writelane_b32 v253, s7, 1
	s_add_u32 s6, s78, 0x1700
	s_addc_u32 s7, s79, 0
	v_writelane_b32 v253, s6, 2
	v_mov_b32_e32 v162, 0x3f317218
	v_mov_b32_e32 v200, 0x7f800000
	v_writelane_b32 v253, s7, 3
	s_add_u32 s6, s78, 0x1800
	s_addc_u32 s7, s79, 0
	v_writelane_b32 v253, s6, 4
	v_mov_b32_e32 v201, 0x7fc00000
	v_mov_b32_e32 v202, 0xff800000
	v_writelane_b32 v253, s7, 5
	s_add_u32 s6, s78, 0x1900
	s_addc_u32 s7, s79, 0
	v_writelane_b32 v253, s6, 6
	v_mov_b32_e32 v203, 0x3000
	v_mov_b32_e32 v204, 0x1800
	v_writelane_b32 v253, s7, 7
	s_add_u32 s6, s78, 0x1a00
	s_addc_u32 s7, s79, 0
	v_writelane_b32 v253, s6, 8
	v_mov_b32_e32 v205, 0x3fff
	v_mov_b32_e32 v206, 0xf149f2ca
	v_writelane_b32 v253, s7, 9
	s_add_u32 s6, s78, 0x1b00
	s_addc_u32 s7, s79, 0
	v_writelane_b32 v253, s6, 10
	v_mov_b32_e32 v207, 0x60
	v_mov_b32_e32 v208, 0xe400
	v_writelane_b32 v253, s7, 11
	s_add_u32 s6, s78, 0x1c00
	s_addc_u32 s7, s79, 0
	v_writelane_b32 v253, s6, 12
	v_mov_b32_e32 v209, 0xa000
	v_mov_b64_e32 v[164:165], 0x400
	v_writelane_b32 v253, s7, 13
	s_add_u32 s6, s78, 0x1d00
	s_addc_u32 s7, s79, 0
	v_writelane_b32 v253, s6, 14
	v_mov_b64_e32 v[166:167], 0x3ff
	s_movk_i32 s75, 0x800
	v_writelane_b32 v253, s7, 15
	s_add_u32 s6, s78, 0x1e00
	s_addc_u32 s7, s79, 0
	v_writelane_b32 v253, s6, 16
	s_movk_i32 s77, 0x6000
	s_mov_b32 s71, 0x44800000
	v_writelane_b32 v253, s7, 17
	s_add_u32 s6, s78, 0x1f00
	s_addc_u32 s7, s79, 0
	v_writelane_b32 v253, s6, 18
	s_movk_i32 s73, 0x3000
	s_mov_b32 s69, 0x60000
	v_writelane_b32 v253, s7, 19
	s_add_u32 s6, s78, 0x2000
	s_addc_u32 s7, s79, 0
	v_writelane_b32 v253, s6, 20
	s_mov_b32 s68, 0xbe800000
	s_movk_i32 s70, 0x110
	v_writelane_b32 v253, s7, 21
	s_add_u32 s6, s78, 0x2100
	s_addc_u32 s7, s79, 0
	v_writelane_b32 v253, s6, 22
	s_mov_b64 s[30:31], 0x1000
	s_nop 0
	v_writelane_b32 v253, s7, 23
	s_add_u32 s6, s78, 0x2200
	s_addc_u32 s7, s79, 0
	v_writelane_b32 v253, s6, 24
	s_nop 1
	v_writelane_b32 v253, s7, 25
	s_add_u32 s6, s78, 0x2300
	s_addc_u32 s7, s79, 0
	v_writelane_b32 v253, s6, 26
	s_cmp_eq_u32 s2, 15
	s_nop 0
	v_writelane_b32 v253, s7, 27
	s_cselect_b64 s[6:7], -1, 0
	v_writelane_b32 v253, s6, 28
	s_cmp_eq_u32 s2, 14
	s_nop 0
	v_writelane_b32 v253, s7, 29
	s_cselect_b64 s[6:7], -1, 0
	v_writelane_b32 v253, s6, 30
	s_cmp_eq_u32 s2, 13
	s_nop 0
	v_writelane_b32 v253, s7, 31
	s_cselect_b64 s[6:7], -1, 0
	v_writelane_b32 v253, s6, 32
	s_cmp_eq_u32 s2, 12
	s_nop 0
	v_writelane_b32 v253, s7, 33
	s_cselect_b64 s[6:7], -1, 0
	v_writelane_b32 v253, s6, 34
	s_cmp_eq_u32 s2, 11
	s_nop 0
	v_writelane_b32 v253, s7, 35
	s_cselect_b64 s[6:7], -1, 0
	v_writelane_b32 v253, s6, 36
	s_cmp_eq_u32 s2, 10
	s_nop 0
	v_writelane_b32 v253, s7, 37
	s_cselect_b64 s[6:7], -1, 0
	v_writelane_b32 v253, s6, 38
	s_cmp_eq_u32 s2, 9
	s_nop 0
	v_writelane_b32 v253, s7, 39
	s_cselect_b64 s[6:7], -1, 0
	v_writelane_b32 v253, s6, 40
	s_cmp_eq_u32 s2, 8
	s_nop 0
	v_writelane_b32 v253, s7, 41
	s_cselect_b64 s[6:7], -1, 0
	v_writelane_b32 v253, s6, 42
	s_cmp_eq_u32 s2, 7
	s_nop 0
	v_writelane_b32 v253, s7, 43
	s_cselect_b64 s[6:7], -1, 0
	v_writelane_b32 v253, s6, 44
	s_cmp_eq_u32 s2, 6
	s_nop 0
	v_writelane_b32 v253, s7, 45
	s_cselect_b64 s[6:7], -1, 0
	v_writelane_b32 v253, s6, 46
	s_cmp_eq_u32 s2, 5
	s_nop 0
	v_writelane_b32 v253, s7, 47
	s_cselect_b64 s[6:7], -1, 0
	v_writelane_b32 v253, s6, 48
	s_cmp_eq_u32 s2, 4
	s_nop 0
	v_writelane_b32 v253, s7, 49
	s_cselect_b64 s[6:7], -1, 0
	v_writelane_b32 v253, s6, 50
	s_cmp_eq_u32 s2, 3
	s_nop 0
	v_writelane_b32 v253, s7, 51
	s_cselect_b64 s[6:7], -1, 0
	v_writelane_b32 v253, s6, 52
	s_cmp_eq_u32 s2, 2
	s_nop 0
	v_writelane_b32 v253, s7, 53
	s_cselect_b64 s[6:7], -1, 0
	v_writelane_b32 v253, s6, 54
	s_cmp_eq_u32 s2, 1
	s_nop 0
	v_writelane_b32 v253, s7, 55
	s_cselect_b64 s[6:7], -1, 0
	v_writelane_b32 v253, s6, 56
	s_cmp_eq_u32 s2, 0
	s_nop 0
	v_writelane_b32 v253, s7, 57
	s_cselect_b64 s[6:7], -1, 0
	s_lshl_b32 s2, s2, 8
	s_add_u32 s2, s20, s2
	v_writelane_b32 v253, s6, 58
	s_addc_u32 s3, s21, 0
	s_nop 0
	v_writelane_b32 v253, s7, 59
	s_add_u32 s6, s2, 0x1400
	s_addc_u32 s7, s3, 0
	v_writelane_b32 v253, s6, 60
	s_add_u32 s2, s2, 0x2400
	s_addc_u32 s3, s3, 0
	v_writelane_b32 v253, s7, 61
	v_writelane_b32 v253, s2, 62
	s_nop 1
	v_writelane_b32 v253, s3, 63
	s_add_u32 s2, s78, 0x4400
	s_addc_u32 s3, s79, 0
	v_writelane_b32 v254, s2, 0
	s_nop 1
	v_writelane_b32 v254, s3, 1
	s_add_u32 s2, s78, 0x4500
	s_addc_u32 s3, s79, 0
	v_writelane_b32 v254, s2, 2
	s_cmpk_lt_i32 s5, 0x400
	s_movk_i32 s78, 0x90
	v_writelane_b32 v254, s3, 3
	s_cselect_b64 s[2:3], -1, 0
	v_writelane_b32 v254, s2, 4
	s_mov_b32 s79, 0xf800000
	s_nop 0
	v_writelane_b32 v254, s3, 5
	s_sub_u32 s2, 0x400, s5
; #define SEAM(k) do { if ((k) + 1 < hi) xcd_barrier(bar); } while (0)
;     __host__ __device__ bool next(int i, Unit& u) const {
;         if ((long)i * G + c >= nwg) return false;
;         const long L = (long)((REV && nwg % G == 0) ? nwg / G - 1 - i : i) * G + c;
;         int wgid = (int)L; { const int q = nwg / NXCD, r = nwg % NXCD, xcd = wgid % NXCD, off = wgid / NXCD; wgid = (xcd < r ? xcd * (q + 1) : r * (q + 1) + (xcd - r) * q) + off; }
;         const int nig = GH * nN, gid = wgid / nig, fm = gid * GH, gsz = (nM % GH == 0) ? GH : ((nM - fm) < GH ? (nM - fm) : GH);
;         u.pm = fm + ((wgid % nig) % gsz); u.pn = (wgid % nig) / gsz; return true;
; __global__ void __launch_bounds__(NTHR, 2) fwd_kernel(Args args) {
;     ...
;             pg8::Gemm g{XB, (const bf16*)(ws + (second ? WS_WGU2 : WS_WGU1)), M, NGU, DM}; pg8::StaticOrder S; S.init(M, NGU, G, bx);
;             pg8::EpiSwiglu E{HP, DFF, rs_in, RS_INV / DM, NORM_EPS};
;             pg8::gemm_phase<pg8::EpiSwiglu, pg8::StaticOrder, true, true>(lds, g, S, E);
;             SEAM(base + 1);
;         }
;         if (IN(base + 2)) {
;             pg8::Gemm g{HP, (const bf16*)(ws + (second ? WS_WD2 : WS_WD1)), M, DM, DFF}; pg8::StaticOrderT<4, true> S; S.init(M, DM, G, bx);
;             pg8::EpiResid E{XB, (unsigned char*)(ws + WS_XLO), rs_out, DM, 0.5f};
;             pg8::gemm_phase<pg8::EpiResid, pg8::StaticOrderT<4, true>, true, true>(lds, g, S, E);
;             SEAM(base + 2);
;         }
;         if (!second) {
;             if (IN(base + 3)) {
;                 pg8::Gemm g{XB, (const bf16*)(ws + WS_WIN), M, NPROJ, DM}; pg8::StaticOrder S; S.init(M, NPROJ, G, bx);
	v_writelane_b32 v254, s4, 6
	s_subb_u32 s3, 0, s4
	v_writelane_b32 v254, s2, 7
	s_cmpk_lt_i32 s5, 0xc00
	s_nop 0
	v_writelane_b32 v254, s3, 8
	s_cselect_b64 s[2:3], -1, 0
	v_writelane_b32 v254, s2, 9
	s_nop 1
	v_writelane_b32 v254, s3, 10
	s_and_b32 s2, s96, 1
	s_cmp_eq_u32 s2, 0
	s_cselect_b64 s[4:5], -1, 0
	v_writelane_b32 v254, s4, 11
	s_cmp_eq_u32 s2, 1
	s_cselect_b64 s[2:3], -1, 0
	v_writelane_b32 v254, s5, 12
	v_writelane_b32 v254, s2, 13
	s_cmpk_lt_i32 s96, 0x200
	s_nop 0
	v_writelane_b32 v254, s3, 14
	s_cselect_b64 s[2:3], -1, 0
	v_writelane_b32 v254, s2, 15
	s_nop 1
	v_writelane_b32 v254, s3, 16
	s_lshl_b32 s2, s96, 7
	s_and_b32 s2, s2, 0x180
	v_writelane_b32 v254, s2, 17
	s_ashr_i32 s2, s96, 10
	s_ashr_i32 s3, s2, 31
	s_lshl_b64 s[4:5], s[2:3], 14
	s_lshl_b32 s2, s96, 4
	s_and_b32 s3, s2, 0x3fc0
	s_or_b32 s6, s4, s3
	s_cmpk_lt_i32 s96, 0x800
	s_cselect_b64 s[8:9], -1, 0
	v_writelane_b32 v254, s8, 18
	s_and_b32 s3, s2, 0x3ff0
	s_add_i32 s7, s3, 0xffffff80
	v_writelane_b32 v254, s9, 19
	v_writelane_b32 v254, s7, 20
	s_or_b32 s7, s4, 16
	v_writelane_b32 v254, s7, 21
	s_or_b32 s7, s4, 24
	v_writelane_b32 v254, s7, 22
	v_writelane_b32 v254, s3, 23
	s_addk_i32 s3, 0xffa0
	s_cmpk_lt_i32 s96, 0x104
	v_writelane_b32 v254, s3, 24
	s_cselect_b64 s[8:9], -1, 0
	s_and_b32 s3, s2, 0x3f00
	s_and_b32 s20, s96, 15
	v_writelane_b32 v254, s8, 25
	s_or_b32 s3, s3, s20
	s_cmpk_lt_i32 s96, 0x400
	v_writelane_b32 v254, s9, 26
	v_writelane_b32 v254, s3, 27
	s_cselect_b64 s[8:9], -1, 0
	v_writelane_b32 v254, s8, 28
	s_cmpk_gt_i32 s96, 0x3ff
	s_mul_i32 s20, s1, 0x81
	v_writelane_b32 v254, s9, 29
	s_cselect_b64 s[8:9], -1, 0
	s_lshl_b32 s3, s1, 7
	s_cmp_lt_i32 s1, 0
	s_movk_i32 s7, 0x2c1
	s_cselect_b32 s3, s20, s3
	s_cselect_b32 s20, s7, 0x2c0
	s_mul_i32 s20, s1, s20
	s_movk_i32 s7, 0x181
	s_cselect_b32 s21, s7, 0x180
	s_add_i32 s20, s20, s0
	s_mul_hi_i32 s22, s20, 0x2e8ba2e9
	s_lshr_b32 s23, s22, 31
	s_ashr_i32 s22, s22, 6
	s_add_i32 s22, s22, s23
	s_mul_i32 s23, s22, 0x160
	s_sub_i32 s20, s20, s23
	s_bfe_u32 s23, s20, 0x3001c
	s_mul_i32 s1, s1, s21
	s_add_i32 s23, s20, s23
	s_add_i32 s1, s1, s0
	s_and_b32 s24, s23, 0xfff8
	s_mul_hi_i32 s21, s1, 0x2aaaaaab
	s_sub_i32 s20, s20, s24
	s_lshr_b32 s24, s21, 31
	s_ashr_i32 s21, s21, 5
	s_add_i32 s21, s21, s24
	s_mul_i32 s24, s21, 0xc0
	s_abs_i32 s28, s62
	s_sub_i32 s1, s1, s24
	v_cvt_f32_u32_e32 v1, s28
	s_bfe_u32 s24, s1, 0x3001c
	s_add_i32 s24, s1, s24
	s_and_b32 s25, s24, 0xfff8
	s_add_i32 s0, s3, s0
	s_sub_i32 s25, s1, s25
	s_ashr_i32 s1, s0, 31
	v_rcp_iflag_f32_e32 v1, v1
	s_lshr_b32 s1, s1, 27
	s_add_i32 s3, s0, s1
	s_and_b32 s1, s3, 0xffe0
	s_sub_i32 s0, s0, s1
	v_mul_f32_e32 v1, 0x4f7ffffe, v1
	s_bfe_i32 s1, s0, 0x80000
	v_cvt_u32_f32_e32 v1, v1
	s_bfe_u32 s1, s1, 0x2000d
	s_add_i32 s26, s0, s1
	s_and_b32 s1, s26, 0xfc
	s_sub_i32 s27, s0, s1
	s_sub_i32 s0, 0, s28
	v_readfirstlane_b32 s1, v1
	s_mul_i32 s0, s0, s1
	s_mul_hi_u32 s0, s1, s0
	v_writelane_b32 v254, s8, 30
	s_add_i32 s29, s1, s0
	s_lshl_b32 s0, s22, 3
	s_sext_i32_i16 s1, s23
	s_sext_i32_i16 s20, s20
	v_writelane_b32 v254, s9, 31
	s_add_i32 s10, s0, s20
	s_ashr_i32 s0, s1, 3
	v_writelane_b32 v254, s0, 32
	s_lshr_b32 s0, s1, 3
	s_bfe_i64 s[0:1], s[0:1], 0x100000
	s_lshl_b64 s[0:1], s[0:1], 20
	v_writelane_b32 v254, s0, 33
	s_sext_i32_i16 s20, s25
	s_mov_b32 s8, s10
	v_writelane_b32 v254, s1, 34
	s_lshl_b32 s0, s21, 3
	s_sext_i32_i16 s1, s24
	s_add_i32 s12, s0, s20
	s_ashr_i32 s0, s1, 3
	v_writelane_b32 v254, s0, 35
	s_lshr_b32 s0, s1, 3
	s_bfe_i64 s[0:1], s[0:1], 0x100000
	s_lshl_b64 s[0:1], s[0:1], 20
	v_writelane_b32 v254, s0, 36
	s_ashr_i32 s11, s10, 31
	s_ashr_i32 s13, s12, 31
	v_writelane_b32 v254, s1, 37
	s_ashr_i32 s0, s3, 5
	s_bfe_i32 s1, s26, 0x80000
	s_lshl_b32 s0, s0, 2
	s_sext_i32_i16 s1, s1
	s_sext_i32_i8 s3, s27
	s_add_i32 s14, s0, s3
	s_ashr_i32 s0, s1, 2
	v_writelane_b32 v254, s0, 38
	s_lshr_b32 s0, s1, 2
	s_bfe_i64 s[0:1], s[0:1], 0x100000
	s_lshl_b64 s[0:1], s[0:1], 20
	v_writelane_b32 v254, s0, 39
	s_ashr_i32 s15, s14, 31
	s_movk_i32 s21, 0x80
	v_writelane_b32 v254, s1, 40
	v_writelane_b32 v254, s8, 41
	s_lshr_b32 s0, s29, 22
	s_mul_i32 s1, s0, s28
	v_writelane_b32 v254, s9, 42
	s_lshl_b64 s[8:9], s[10:11], 20
	v_writelane_b32 v254, s8, 43
	s_sub_i32 s1, 0x400, s1
	s_sub_i32 s3, s1, s28
	v_writelane_b32 v254, s9, 44
	s_mov_b32 s8, s12
	v_writelane_b32 v254, s8, 45
	s_add_i32 s20, s0, 1
	v_mbcnt_lo_u32_b32 v1, -1, 0
	v_writelane_b32 v254, s9, 46
	s_lshl_b64 s[8:9], s[12:13], 20
	v_writelane_b32 v254, s8, 47
	v_mbcnt_hi_u32_b32 v199, -1, v1
	s_mov_b32 s25, 0
	v_writelane_b32 v254, s9, 48
	s_mov_b32 s8, s14
	v_writelane_b32 v254, s8, 49
	s_nop 1
	v_writelane_b32 v254, s9, 50
	s_lshl_b64 s[8:9], s[14:15], 20
	s_cmp_ge_u32 s1, s28
	s_cselect_b32 s1, s3, s1
	s_cselect_b32 s0, s20, s0
	s_sub_i32 s3, s1, s28
	s_add_i32 s20, s0, 1
	s_cmp_ge_u32 s1, s28
	s_cselect_b32 s1, s3, s1
	v_writelane_b32 v254, s8, 51
	s_cselect_b32 s0, s20, s0
	s_cmp_eq_u32 s1, 0
	v_writelane_b32 v254, s9, 52
	s_cselect_b64 s[8:9], -1, 0
	s_xor_b32 s0, s0, s63
	v_writelane_b32 v254, s8, 53
	s_sub_i32 s0, s0, s63
	s_add_i32 s1, s0, -1
	v_writelane_b32 v254, s9, 54
	v_writelane_b32 v254, s1, 55
	v_writelane_b32 v254, s0, 56
	s_mul_i32 s0, s0, s62
	s_cmpk_eq_i32 s0, 0x400
	s_cselect_b64 s[0:1], -1, 0
	v_writelane_b32 v254, s0, 57
	s_ashr_i32 s97, s96, 31
	s_mov_b64 s[28:29], 0x80
	v_writelane_b32 v254, s1, 58
	s_lshl_b64 s[0:1], s[96:97], 17
	s_add_u32 s0, s0, 0x32a00080
	v_writelane_b32 v254, s0, 59
	s_addc_u32 s0, s1, 0
	v_writelane_b32 v254, s0, 60
	v_writelane_b32 v254, s4, 61
	s_mov_b32 s7, s5
	s_add_i32 s0, s96, s62
	v_writelane_b32 v254, s5, 62
	v_writelane_b32 v254, s6, 63
	s_lshl_b32 s0, s0, 4
	s_add_i32 s76, 0, 0x11400
	v_writelane_b32 v255, s7, 0
	v_writelane_b32 v255, s0, 1
	s_sub_i32 s0, s2, 64
	v_writelane_b32 v255, s0, 2
	s_lshl_b32 s0, s62, 4
	v_writelane_b32 v255, s0, 3
	s_add_i32 s0, s96, 0xffffff7c
	v_writelane_b32 v255, s0, 4
	v_readlane_b32 s0, v252, 38
	s_sub_i32 s0, s0, 32
	v_cmp_eq_u32_e64 s[2:3], 0, v0
	v_writelane_b32 v255, s0, 5
	s_mov_b32 s0, s96
	v_writelane_b32 v255, s0, 6
	s_nop 1
	v_writelane_b32 v255, s1, 7
	s_lshl_b32 s0, s96, 8
	v_writelane_b32 v255, s0, 8
	s_lshl_b32 s0, s62, 8
	v_writelane_b32 v255, s0, 9
	s_add_i32 s0, 0, 0x23040
	v_writelane_b32 v255, s0, 10
	s_add_i32 s0, 0, 0x10400
	v_writelane_b32 v255, s0, 11
	s_add_i32 s0, 0, 0x20800
	v_writelane_b32 v255, s0, 12
	v_writelane_b32 v255, s2, 13
	s_mov_b32 s0, 0
	s_nop 0
	v_writelane_b32 v255, s3, 14
	v_readlane_b32 s2, v252, 58
	v_readlane_b32 s3, v252, 59
	v_mov_b32_e32 v247, 0
	s_nop 4
	global_load_dword v247, v247, s[2:3] offset:4 sc1
	s_waitcnt vmcnt(0)
	v_readfirstlane_b32 s2, v247
	s_bcnt1_i32_b32 s2, s2
	s_cmp_eq_u32 s2, 1
	s_cselect_b32 s2, 1, 0
	v_writelane_b32 v255, s2, 41
	s_lshl_b64 s[2:3], s[62:63], 17
	v_writelane_b32 v255, s2, 15
	s_nop 1
	v_writelane_b32 v255, s3, 16
	s_branch .LBB0_202

; __device__ __forceinline__ unsigned xb_ld(unsigned* p)              { return __hip_atomic_load(p, __ATOMIC_RELAXED, __HIP_MEMORY_SCOPE_AGENT); }
; __device__ __forceinline__ unsigned xb_add(unsigned* p, unsigned v) { return __hip_atomic_fetch_add(p, v, __ATOMIC_RELAXED, __HIP_MEMORY_SCOPE_AGENT); }
; #define XB_SPIN(cond, bar) do { unsigned _sp = 0; while (cond) { __builtin_amdgcn_s_sleep(1); \
;     if ((++_sp & 255u) == 0u) { if (xb_ld(&(bar)[XB_TMO])) break; if (_sp > XB_SPIN_CAP) { atomicAdd(&(bar)[XB_TMO], 1u); break; } } } } while (0)
; #define SEAM(k) do { if ((k) + 1 < hi) xcd_barrier(bar); } while (0)
; __device__ __forceinline__ void xcd_barrier(const XcdBarrier& b) {
;     ...
;         const unsigned old = xb_add(&bar[XB_XSUB(b.x)], 1u);
;         const unsigned gen = old / nloc;
;         if (old + 1u == (gen + 1u) * nloc) {
;             __builtin_amdgcn_fence(__ATOMIC_RELEASE, "agent");
;             asm volatile("s_waitcnt vmcnt(0)" ::: "memory");
;             const unsigned og = xb_add(&bar[XB_TOP], 1u);
;             const unsigned tg = og / nx;
;             if (og + 1u == (tg + 1u) * nx) xb_add(&bar[XB_TOPGEN], 1u);
;             else XB_SPIN(xb_ld(&bar[XB_TOPGEN]) == tg, bar);
; __global__ void __launch_bounds__(NTHR, 2) fwd_kernel(Args args) {
;     ...
;             SEAM(base + 1);
.LBB0_254:
	s_andn2_saveexec_b64 s[34:35], s[36:37]
	s_cbranch_execz .LBB0_272
	s_mov_b64 s[36:37], exec
	v_readlane_b32 s3, v255, 41
	s_cmp_lg_u32 s3, 0
	s_cbranch_scc1 .Lxloc_gu
	buffer_wbl2 sc1
	s_waitcnt lgkmcnt(0)
	s_waitcnt vmcnt(0)
	v_mbcnt_lo_u32_b32 v1, s36, 0
	v_mbcnt_hi_u32_b32 v1, s37, v1
	v_cmp_eq_u32_e32 vcc, 0, v1
	s_and_saveexec_b64 s[38:39], vcc
	s_cbranch_execz .LBB0_257
	s_bcnt1_i32_b64 s3, s[36:37]
	v_readlane_b32 s4, v254, 0
	v_mov_b32_e32 v3, s3
	v_readlane_b32 s5, v254, 1
	s_nop 4
	global_atomic_add v3, v5, v3, s[4:5] sc0

; __device__ __forceinline__ unsigned xb_add(unsigned* p, unsigned v) { return __hip_atomic_fetch_add(p, v, __ATOMIC_RELAXED, __HIP_MEMORY_SCOPE_AGENT); }
; __device__ __forceinline__ void xcd_barrier(const XcdBarrier& b) {
;     ...
;             __builtin_amdgcn_fence(__ATOMIC_ACQUIRE, "agent");
;             xb_add(&bar[XB_XGEN(b.x)], 1u);
;             asm volatile("s_waitcnt vmcnt(0)" ::: "memory");
.Lxloc_gu:
	v_readlane_b32 s4, v253, 62
	v_readlane_b32 s5, v253, 63
	s_waitcnt vmcnt(0)
	buffer_inv sc1
	s_nop 2
	global_atomic_add v5, v195, s[4:5]
	s_waitcnt vmcnt(0)

; __device__ __forceinline__ unsigned xb_ld(unsigned* p)              { return __hip_atomic_load(p, __ATOMIC_RELAXED, __HIP_MEMORY_SCOPE_AGENT); }
; __device__ __forceinline__ unsigned xb_add(unsigned* p, unsigned v) { return __hip_atomic_fetch_add(p, v, __ATOMIC_RELAXED, __HIP_MEMORY_SCOPE_AGENT); }
; #define XB_SPIN(cond, bar) do { unsigned _sp = 0; while (cond) { __builtin_amdgcn_s_sleep(1); \
;     if ((++_sp & 255u) == 0u) { if (xb_ld(&(bar)[XB_TMO])) break; if (_sp > XB_SPIN_CAP) { atomicAdd(&(bar)[XB_TMO], 1u); break; } } } } while (0)
; #define SEAM(k) do { if ((k) + 1 < hi) xcd_barrier(bar); } while (0)
; __device__ __forceinline__ void xcd_barrier(const XcdBarrier& b) {
;     ...
;         const unsigned old = xb_add(&bar[XB_XSUB(b.x)], 1u);
;         const unsigned gen = old / nloc;
;         if (old + 1u == (gen + 1u) * nloc) {
;             __builtin_amdgcn_fence(__ATOMIC_RELEASE, "agent");
;             asm volatile("s_waitcnt vmcnt(0)" ::: "memory");
;             const unsigned og = xb_add(&bar[XB_TOP], 1u);
;             const unsigned tg = og / nx;
;             if (og + 1u == (tg + 1u) * nx) xb_add(&bar[XB_TOPGEN], 1u);
;             else XB_SPIN(xb_ld(&bar[XB_TOPGEN]) == tg, bar);
; __global__ void __launch_bounds__(NTHR, 2) fwd_kernel(Args args) {
;     ...
;             SEAM(base + 2);
.LBB0_353:
	s_andn2_saveexec_b64 s[2:3], s[36:37]
	s_cbranch_execz .LBB0_371
	s_mov_b64 s[36:37], exec
	v_readlane_b32 s2, v255, 41
	s_cmp_lg_u32 s2, 0
	s_cbranch_scc0 .Lxfull_dn
	v_readlane_b32 s2, v255, 17
	s_cmp_eq_u32 s2, 7
	s_cbranch_scc1 .Lxfull_dn
	s_bitcmp1_b32 s2, 0
	s_cbranch_scc1 .Lxloc_dn
.Lxfull_dn:
	buffer_wbl2 sc1
	s_waitcnt lgkmcnt(0)
	s_waitcnt vmcnt(0)
	v_mbcnt_lo_u32_b32 v1, s36, 0
	v_mbcnt_hi_u32_b32 v1, s37, v1
	v_cmp_eq_u32_e32 vcc, 0, v1
	s_and_saveexec_b64 s[38:39], vcc
	s_cbranch_execz .LBB0_356
	s_bcnt1_i32_b64 s2, s[36:37]
	v_mov_b32_e32 v3, s2
	v_readlane_b32 s2, v254, 0
	v_readlane_b32 s3, v254, 1
	s_nop 4
	global_atomic_add v3, v5, v3, s[2:3] sc0

; __device__ __forceinline__ unsigned xb_add(unsigned* p, unsigned v) { return __hip_atomic_fetch_add(p, v, __ATOMIC_RELAXED, __HIP_MEMORY_SCOPE_AGENT); }
; __device__ __forceinline__ void xcd_barrier(const XcdBarrier& b) {
;     ...
;             __builtin_amdgcn_fence(__ATOMIC_ACQUIRE, "agent");
;             xb_add(&bar[XB_XGEN(b.x)], 1u);
;             asm volatile("s_waitcnt vmcnt(0)" ::: "memory");
.Lxloc_dn:
	v_readlane_b32 s2, v253, 62
	v_readlane_b32 s3, v253, 63
	s_waitcnt vmcnt(0)
	buffer_inv sc1
	s_nop 2
	global_atomic_add v5, v195, s[2:3]
	s_waitcnt vmcnt(0)

; __global__ void __launch_bounds__(NTHR, 2) fwd_kernel(Args args) {
;     ...
;     for (int f = 0; f < 2 * DEPTH; ++f) {
.Lxto200_wo:
	s_getpc_b64 s[98:99]

; __device__ __forceinline__ unsigned xb_ld(unsigned* p)              { return __hip_atomic_load(p, __ATOMIC_RELAXED, __HIP_MEMORY_SCOPE_AGENT); }
; __device__ __forceinline__ unsigned xb_add(unsigned* p, unsigned v) { return __hip_atomic_fetch_add(p, v, __ATOMIC_RELAXED, __HIP_MEMORY_SCOPE_AGENT); }
; #define XB_SPIN(cond, bar) do { unsigned _sp = 0; while (cond) { __builtin_amdgcn_s_sleep(1); \
;     if ((++_sp & 255u) == 0u) { if (xb_ld(&(bar)[XB_TMO])) break; if (_sp > XB_SPIN_CAP) { atomicAdd(&(bar)[XB_TMO], 1u); break; } } } } while (0)
; #define SEAM(k) do { if ((k) + 1 < hi) xcd_barrier(bar); } while (0)
; __device__ __forceinline__ void xcd_barrier(const XcdBarrier& b) {
;     ...
;         const unsigned old = xb_add(&bar[XB_XSUB(b.x)], 1u);
;         const unsigned gen = old / nloc;
;         if (old + 1u == (gen + 1u) * nloc) {
;             __builtin_amdgcn_fence(__ATOMIC_RELEASE, "agent");
;             asm volatile("s_waitcnt vmcnt(0)" ::: "memory");
;             const unsigned og = xb_add(&bar[XB_TOP], 1u);
;             const unsigned tg = og / nx;
;             if (og + 1u == (tg + 1u) * nx) xb_add(&bar[XB_TOPGEN], 1u);
;             else XB_SPIN(xb_ld(&bar[XB_TOPGEN]) == tg, bar);
;             __builtin_amdgcn_fence(__ATOMIC_ACQUIRE, "agent");
;             xb_add(&bar[XB_XGEN(b.x)], 1u);
;             asm volatile("s_waitcnt vmcnt(0)" ::: "memory");
; __global__ void __launch_bounds__(NTHR, 2) fwd_kernel(Args args) {
;     ...
;                 SEAM(base + 7);
.LBB0_1793:
	s_mov_b64 s[22:23], exec
	v_readlane_b32 s2, v255, 41
	s_cmp_lg_u32 s2, 0
	s_cbranch_scc0 .Lxfull_wo
	v_readlane_b32 s2, v253, 62
	v_readlane_b32 s3, v253, 63
	s_waitcnt vmcnt(0)
	buffer_inv sc1
	s_nop 2
	global_atomic_add v5, v195, s[2:3]
	s_waitcnt vmcnt(0)
	s_branch .Lxto200_wo
.Lxfull_wo:
	buffer_wbl2 sc1
	s_waitcnt lgkmcnt(0)
	s_waitcnt vmcnt(0)
	v_mbcnt_lo_u32_b32 v1, s22, 0
	v_mbcnt_hi_u32_b32 v1, s23, v1
	v_cmp_eq_u32_e32 vcc, 0, v1
	s_and_saveexec_b64 s[26:27], vcc
	s_cbranch_execz .LBB0_1795
	s_bcnt1_i32_b64 s2, s[22:23]
	v_mov_b32_e32 v3, s2
	v_readlane_b32 s2, v254, 0
	v_readlane_b32 s3, v254, 1
	s_nop 4
	global_atomic_add v3, v5, v3, s[2:3] sc0
